# P7 prologue de-serialised: the 8 S-fragment load rounds hoisted into dead VGPRs with counted waits and v_mov copy-in (was 8 dependent load-wait-pack rounds); on top of v_p12_lw
# speedup vs baseline: 1.0060x; 1.0060x over previous
; __device__ __forceinline__ unsigned pk2(float lo, float hi) { return f2bf(lo) | (f2bf(hi) << 16); }
; __device__ __forceinline__ void phase_scan2z(const Params& p) {
;     ...
;             for (int ks = 0; ks < 2; ++ks) { u32x4 w = (u32x4){0u, 0u, 0u, 0u};
;                 if (ch > 0) { const float* sp = ST + ((size_t)(u - 1) * 2) * 4096 + (16 * c + lr) * 64 + 32 * ks + 8 * lq; const f32x4 x0 = *(const f32x4*)sp, x1 = *(const f32x4*)(sp + 4);
;                     w.x = pk2(x0[0], x0[1]); w.y = pk2(x0[2], x0[3]); w.z = pk2(x1[0], x1[1]); w.w = pk2(x1[2], x1[3]); }
;                 Sf[c][ks] = __builtin_bit_cast(bf16x8, w); }
.LBB0_1351:
	v_ashrrev_i32_e32 v113, 31, v112
	v_lshrrev_b32_e32 v0, 26, v113
	v_add_u32_e32 v35, v112, v0
	v_and_b32_e32 v0, 0xffffffc0, v35
	v_sub_u32_e32 v66, v112, v0
	v_mov_b32_e32 v0, v117
	v_cmp_lt_i32_e64 s[4:5], 0, v66
	v_ashrrev_i32_e32 v34, 4, v0
	v_and_b32_e32 v88, 15, v0
	s_waitcnt lgkmcnt(0)
	v_lshlrev_b64 v[0:1], 15, v[112:113]
	v_lshlrev_b32_e32 v64, 3, v34
	v_lshl_add_u64 v[0:1], s[18:19], 0, v[0:1]
	v_ashrrev_i32_e32 v65, 31, v64
	v_lshl_add_u64 v[0:1], v[64:65], 2, v[0:1]
	v_lshlrev_b32_e32 v114, 8, v88
	v_lshl_add_u64 v[0:1], v[0:1], 0, v[114:115]
	v_lshl_add_u64 v[32:33], v[0:1], 0, s[38:39]
	s_and_saveexec_b64 s[0:1], s[4:5]
	s_cbranch_execz .Lp7_h_done
	v_mov_b32_e32 v242, 0x1000
	v_mov_b32_e32 v243, 0
	global_load_dwordx4 v[200:203], v[32:33], off
	global_load_dwordx4 v[204:207], v[32:33], off offset:16
	global_load_dwordx4 v[208:211], v[32:33], off offset:128
	global_load_dwordx4 v[212:215], v[32:33], off offset:144
	v_lshl_add_u64 v[240:241], v[32:33], 0, v[242:243]
	global_load_dwordx4 v[216:219], v[240:241], off
	global_load_dwordx4 v[220:223], v[240:241], off offset:16
	global_load_dwordx4 v[224:227], v[240:241], off offset:128
	global_load_dwordx4 v[228:231], v[240:241], off offset:144
	v_lshl_add_u64 v[240:241], v[240:241], 0, v[242:243]
	global_load_dwordx4 v[232:235], v[240:241], off
	global_load_dwordx4 v[236:239], v[240:241], off offset:16
.Lp7_h_done:
	s_or_b64 exec, exec, s[0:1]
	v_mov_b32_e32 v0, v115
	v_mov_b32_e32 v1, v115
	v_mov_b32_e32 v2, v115
	v_mov_b32_e32 v3, v115
	s_and_saveexec_b64 s[0:1], s[4:5]
	s_cbranch_execz .LBB0_1353
	s_waitcnt vmcnt(8)
	v_mov_b32_e32 v0, v200
	v_mov_b32_e32 v1, v201
	v_mov_b32_e32 v2, v202
	v_mov_b32_e32 v3, v203
	v_mov_b32_e32 v4, v204
	v_mov_b32_e32 v5, v205
	v_mov_b32_e32 v6, v206
	v_mov_b32_e32 v7, v207
	global_load_dwordx4 v[200:203], v[240:241], off offset:128
	global_load_dwordx4 v[204:207], v[240:241], off offset:144
	v_bfe_u32 v8, v0, 16, 1
	v_bfe_u32 v10, v2, 16, 1
	v_bfe_u32 v12, v4, 16, 1
	v_bfe_u32 v14, v6, 16, 1
	v_bfe_u32 v9, v1, 16, 1
	v_bfe_u32 v11, v3, 16, 1
	v_bfe_u32 v13, v5, 16, 1
	v_bfe_u32 v15, v7, 16, 1
	v_add3_u32 v0, v0, v8, s33
	v_add3_u32 v2, v2, v10, s33
	v_add3_u32 v4, v4, v12, s33
	v_add3_u32 v6, v6, v14, s33
	v_add3_u32 v1, v1, v9, s33
	v_add3_u32 v3, v3, v11, s33
	v_add3_u32 v5, v5, v13, s33
	v_add3_u32 v7, v7, v15, s33
	v_lshrrev_b32_e32 v0, 16, v0
	v_lshrrev_b32_e32 v2, 16, v2
	v_lshrrev_b32_e32 v4, 16, v4
	v_lshrrev_b32_e32 v6, 16, v6
	v_and_or_b32 v0, v1, s50, v0
	v_and_or_b32 v1, v3, s50, v2
	v_and_or_b32 v2, v5, s50, v4
	v_and_or_b32 v3, v7, s50, v6
.LBB0_1353:
	s_or_b64 exec, exec, s[0:1]
	v_mov_b32_e32 v8, 0
	v_mov_b32_e32 v4, 0
	v_mov_b32_e32 v5, 0
	v_mov_b32_e32 v6, 0
	v_mov_b32_e32 v7, 0
	s_and_saveexec_b64 s[0:1], s[4:5]
	s_cbranch_execz .LBB0_1355
	s_waitcnt vmcnt(8)
	v_mov_b32_e32 v4, v208
	v_mov_b32_e32 v5, v209
	v_mov_b32_e32 v6, v210
	v_mov_b32_e32 v7, v211
	v_mov_b32_e32 v10, v212
	v_mov_b32_e32 v11, v213
	v_mov_b32_e32 v12, v214
	v_mov_b32_e32 v13, v215
	v_lshl_add_u64 v[198:199], v[240:241], 0, v[242:243]
	global_load_dwordx4 v[208:211], v[198:199], off
	global_load_dwordx4 v[212:215], v[198:199], off offset:16
	v_bfe_u32 v9, v4, 16, 1
	v_bfe_u32 v15, v6, 16, 1
	v_bfe_u32 v17, v10, 16, 1
	v_bfe_u32 v18, v11, 16, 1
	v_bfe_u32 v19, v12, 16, 1
	v_bfe_u32 v14, v5, 16, 1
	v_bfe_u32 v16, v7, 16, 1
	v_bfe_u32 v20, v13, 16, 1
	v_add3_u32 v4, v4, v9, s33
	v_add3_u32 v6, v6, v15, s33
	v_add3_u32 v9, v10, v17, s33
	v_add3_u32 v10, v11, v18, s33
	v_add3_u32 v11, v12, v19, s33
	v_add3_u32 v5, v5, v14, s33
	v_add3_u32 v7, v7, v16, s33
	v_add3_u32 v12, v13, v20, s33
	v_lshrrev_b32_e32 v4, 16, v4
	v_lshrrev_b32_e32 v6, 16, v6
	v_lshrrev_b32_e32 v9, 16, v9
	v_lshrrev_b32_e32 v11, 16, v11
	v_and_or_b32 v4, v5, s50, v4
	v_and_or_b32 v5, v7, s50, v6
	v_and_or_b32 v6, v10, s50, v9
	v_and_or_b32 v7, v12, s50, v11
.LBB0_1355:
	s_or_b64 exec, exec, s[0:1]
	v_mov_b32_e32 v9, 0
	v_mov_b32_e32 v10, 0
	v_mov_b32_e32 v11, 0
	s_and_saveexec_b64 s[0:1], s[4:5]
	s_cbranch_execz .LBB0_1357
	v_add_co_u32_e32 v8, vcc, 0x1000, v32
	v_lshl_add_u64 v[12:13], v[32:33], 0, s[40:41]
	s_nop 0
	v_addc_co_u32_e32 v9, vcc, 0, v33, vcc
	s_nop 0
	s_waitcnt vmcnt(8)
	v_mov_b32_e32 v8, v216
	v_mov_b32_e32 v9, v217
	v_mov_b32_e32 v10, v218
	v_mov_b32_e32 v11, v219
	v_mov_b32_e32 v12, v220
	v_mov_b32_e32 v13, v221
	v_mov_b32_e32 v14, v222
	v_mov_b32_e32 v15, v223
	global_load_dwordx4 v[216:219], v[198:199], off offset:128
	global_load_dwordx4 v[220:223], v[198:199], off offset:144
	v_bfe_u32 v16, v8, 16, 1
	v_bfe_u32 v18, v10, 16, 1
	v_bfe_u32 v20, v12, 16, 1
	v_bfe_u32 v22, v14, 16, 1
	v_bfe_u32 v17, v9, 16, 1
	v_bfe_u32 v19, v11, 16, 1
	v_bfe_u32 v21, v13, 16, 1
	v_bfe_u32 v23, v15, 16, 1
	v_add3_u32 v8, v8, v16, s33
	v_add3_u32 v10, v10, v18, s33
	v_add3_u32 v12, v12, v20, s33
	v_add3_u32 v14, v14, v22, s33
	v_add3_u32 v9, v9, v17, s33
	v_add3_u32 v11, v11, v19, s33
	v_add3_u32 v13, v13, v21, s33
	v_add3_u32 v15, v15, v23, s33
	v_lshrrev_b32_e32 v8, 16, v8
	v_lshrrev_b32_e32 v10, 16, v10
	v_lshrrev_b32_e32 v12, 16, v12
	v_lshrrev_b32_e32 v14, 16, v14
	v_and_or_b32 v8, v9, s50, v8
	v_and_or_b32 v9, v11, s50, v10
	v_and_or_b32 v10, v13, s50, v12
	v_and_or_b32 v11, v15, s50, v14
; __device__ __forceinline__ unsigned pk2(float lo, float hi) { return f2bf(lo) | (f2bf(hi) << 16); }
; __device__ __forceinline__ void phase_scan2z(const Params& p) {
;     ...
;             for (int ks = 0; ks < 2; ++ks) { u32x4 w = (u32x4){0u, 0u, 0u, 0u};
;                 if (ch > 0) { const float* sp = ST + ((size_t)(u - 1) * 2) * 4096 + (16 * c + lr) * 64 + 32 * ks + 8 * lq; const f32x4 x0 = *(const f32x4*)sp, x1 = *(const f32x4*)(sp + 4);
;                     w.x = pk2(x0[0], x0[1]); w.y = pk2(x0[2], x0[3]); w.z = pk2(x1[0], x1[1]); w.w = pk2(x1[2], x1[3]); }
;                 Sf[c][ks] = __builtin_bit_cast(bf16x8, w); }
.LBB0_1357:
	s_or_b64 exec, exec, s[0:1]
	v_mov_b32_e32 v12, 0
	v_mov_b32_e32 v16, 0
	v_mov_b32_e32 v17, 0
	v_mov_b32_e32 v18, 0
	v_mov_b32_e32 v19, 0
	s_and_saveexec_b64 s[0:1], s[4:5]
	s_cbranch_execz .LBB0_1359
	v_add_co_u32_e32 v14, vcc, 0x1000, v32
	v_lshl_add_u64 v[18:19], v[32:33], 0, s[42:43]
	s_nop 0
	v_addc_co_u32_e32 v15, vcc, 0, v33, vcc
	s_nop 0
	s_waitcnt vmcnt(8)
	v_mov_b32_e32 v14, v224
	v_mov_b32_e32 v15, v225
	v_mov_b32_e32 v16, v226
	v_mov_b32_e32 v17, v227
	v_mov_b32_e32 v18, v228
	v_mov_b32_e32 v19, v229
	v_mov_b32_e32 v20, v230
	v_mov_b32_e32 v21, v231
	v_bfe_u32 v13, v14, 16, 1
	v_bfe_u32 v22, v15, 16, 1
	v_bfe_u32 v23, v16, 16, 1
	v_bfe_u32 v25, v18, 16, 1
	v_bfe_u32 v26, v19, 16, 1
	v_bfe_u32 v27, v20, 16, 1
	v_bfe_u32 v24, v17, 16, 1
	v_bfe_u32 v28, v21, 16, 1
	v_add3_u32 v13, v14, v13, s33
	v_add3_u32 v14, v15, v22, s33
	v_add3_u32 v15, v16, v23, s33
	v_add3_u32 v16, v18, v25, s33
	v_add3_u32 v18, v19, v26, s33
	v_add3_u32 v19, v20, v27, s33
	v_add3_u32 v17, v17, v24, s33
	v_add3_u32 v20, v21, v28, s33
	v_lshrrev_b32_e32 v13, 16, v13
	v_lshrrev_b32_e32 v15, 16, v15
	v_lshrrev_b32_e32 v21, 16, v16
	v_lshrrev_b32_e32 v19, 16, v19
	v_and_or_b32 v16, v14, s50, v13
	v_and_or_b32 v17, v17, s50, v15
	v_and_or_b32 v18, v18, s50, v21
	v_and_or_b32 v19, v20, s50, v19
.LBB0_1359:
	s_or_b64 exec, exec, s[0:1]
	v_mov_b32_e32 v13, 0
	v_mov_b32_e32 v14, 0
	v_mov_b32_e32 v15, 0
	s_and_saveexec_b64 s[0:1], s[4:5]
	s_cbranch_execz .LBB0_1361
	v_add_co_u32_e32 v12, vcc, 0x2000, v32
	v_lshl_add_u64 v[20:21], v[32:33], 0, s[44:45]
	s_nop 0
	v_addc_co_u32_e32 v13, vcc, 0, v33, vcc
	s_nop 0
	s_waitcnt vmcnt(6)
	v_mov_b32_e32 v12, v232
	v_mov_b32_e32 v13, v233
	v_mov_b32_e32 v14, v234
	v_mov_b32_e32 v15, v235
	v_mov_b32_e32 v20, v236
	v_mov_b32_e32 v21, v237
	v_mov_b32_e32 v22, v238
	v_mov_b32_e32 v23, v239
	v_bfe_u32 v24, v12, 16, 1
	v_bfe_u32 v26, v14, 16, 1
	v_bfe_u32 v28, v20, 16, 1
	v_bfe_u32 v30, v22, 16, 1
	v_bfe_u32 v25, v13, 16, 1
	v_bfe_u32 v27, v15, 16, 1
	v_bfe_u32 v29, v21, 16, 1
	v_bfe_u32 v31, v23, 16, 1
	v_add3_u32 v12, v12, v24, s33
	v_add3_u32 v14, v14, v26, s33
	v_add3_u32 v20, v20, v28, s33
	v_add3_u32 v22, v22, v30, s33
	v_add3_u32 v13, v13, v25, s33
	v_add3_u32 v15, v15, v27, s33
	v_add3_u32 v21, v21, v29, s33
	v_add3_u32 v23, v23, v31, s33
	v_lshrrev_b32_e32 v12, 16, v12
	v_lshrrev_b32_e32 v14, 16, v14
	v_lshrrev_b32_e32 v20, 16, v20
	v_lshrrev_b32_e32 v22, 16, v22
	v_and_or_b32 v12, v13, s50, v12
	v_and_or_b32 v13, v15, s50, v14
	v_and_or_b32 v14, v21, s50, v20
	v_and_or_b32 v15, v23, s50, v22
.LBB0_1361:
	s_or_b64 exec, exec, s[0:1]
	v_mov_b32_e32 v20, 0
	v_mov_b32_e32 v24, 0
	v_mov_b32_e32 v25, 0
	v_mov_b32_e32 v26, 0
	v_mov_b32_e32 v27, 0
	s_and_saveexec_b64 s[0:1], s[4:5]
	s_cbranch_execz .LBB0_1363
	v_add_co_u32_e32 v22, vcc, 0x2000, v32
	v_lshl_add_u64 v[26:27], v[32:33], 0, s[46:47]
	s_nop 0
	v_addc_co_u32_e32 v23, vcc, 0, v33, vcc
	s_nop 0
	s_waitcnt vmcnt(4)
	v_mov_b32_e32 v22, v200
	v_mov_b32_e32 v23, v201
	v_mov_b32_e32 v24, v202
	v_mov_b32_e32 v25, v203
	v_mov_b32_e32 v26, v204
	v_mov_b32_e32 v27, v205
	v_mov_b32_e32 v28, v206
	v_mov_b32_e32 v29, v207
	v_bfe_u32 v21, v22, 16, 1
	v_bfe_u32 v30, v23, 16, 1
	v_bfe_u32 v31, v24, 16, 1
	v_bfe_u32 v37, v26, 16, 1
	v_bfe_u32 v38, v27, 16, 1
	v_bfe_u32 v39, v28, 16, 1
	v_bfe_u32 v36, v25, 16, 1
	v_bfe_u32 v40, v29, 16, 1
	v_add3_u32 v21, v22, v21, s33
	v_add3_u32 v22, v23, v30, s33
	v_add3_u32 v23, v24, v31, s33
	v_add3_u32 v24, v26, v37, s33
	v_add3_u32 v26, v27, v38, s33
	v_add3_u32 v27, v28, v39, s33
	v_add3_u32 v25, v25, v36, s33
	v_add3_u32 v28, v29, v40, s33
	v_lshrrev_b32_e32 v21, 16, v21
	v_lshrrev_b32_e32 v23, 16, v23
	v_lshrrev_b32_e32 v29, 16, v24
	v_lshrrev_b32_e32 v27, 16, v27
	v_and_or_b32 v24, v22, s50, v21
	v_and_or_b32 v25, v25, s50, v23
	v_and_or_b32 v26, v26, s50, v29
	v_and_or_b32 v27, v28, s50, v27
.LBB0_1363:
	s_or_b64 exec, exec, s[0:1]
	v_mov_b32_e32 v21, 0
	v_mov_b32_e32 v22, 0
	v_mov_b32_e32 v23, 0
	s_and_saveexec_b64 s[0:1], s[4:5]
	s_cbranch_execz .LBB0_1365
	v_add_co_u32_e32 v20, vcc, 0x3000, v32
	v_lshl_add_u64 v[28:29], v[32:33], 0, s[48:49]
	s_nop 0
	v_addc_co_u32_e32 v21, vcc, 0, v33, vcc
	s_nop 0
	s_waitcnt vmcnt(2)
	v_mov_b32_e32 v20, v208
	v_mov_b32_e32 v21, v209
	v_mov_b32_e32 v22, v210
	v_mov_b32_e32 v23, v211
	v_mov_b32_e32 v28, v212
	v_mov_b32_e32 v29, v213
	v_mov_b32_e32 v30, v214
	v_mov_b32_e32 v31, v215
	v_bfe_u32 v36, v20, 16, 1
	v_bfe_u32 v38, v22, 16, 1
	v_bfe_u32 v40, v28, 16, 1
	v_bfe_u32 v42, v30, 16, 1
	v_bfe_u32 v37, v21, 16, 1
	v_bfe_u32 v39, v23, 16, 1
	v_bfe_u32 v41, v29, 16, 1
	v_bfe_u32 v43, v31, 16, 1
	v_add3_u32 v20, v20, v36, s33
	v_add3_u32 v22, v22, v38, s33
	v_add3_u32 v28, v28, v40, s33
	v_add3_u32 v30, v30, v42, s33
	v_add3_u32 v21, v21, v37, s33
	v_add3_u32 v23, v23, v39, s33
	v_add3_u32 v29, v29, v41, s33
	v_add3_u32 v31, v31, v43, s33
	v_lshrrev_b32_e32 v20, 16, v20
	v_lshrrev_b32_e32 v22, 16, v22
	v_lshrrev_b32_e32 v28, 16, v28
	v_lshrrev_b32_e32 v30, 16, v30
	v_and_or_b32 v20, v21, s50, v20
	v_and_or_b32 v21, v23, s50, v22
	v_and_or_b32 v22, v29, s50, v28
	v_and_or_b32 v23, v31, s50, v30
.LBB0_1365:
	s_or_b64 exec, exec, s[0:1]
	s_mov_b32 s57, 0
	v_mov_b32_e32 v28, 0
	v_mov_b32_e32 v29, 0
	v_mov_b32_e32 v30, 0
	v_mov_b32_e32 v31, 0
	s_and_saveexec_b64 s[0:1], s[4:5]
	s_cbranch_execz .LBB0_1367
	v_add_co_u32_e32 v28, vcc, 0x3000, v32
	s_nop 1
	v_addc_co_u32_e32 v29, vcc, 0, v33, vcc
	v_lshl_add_u64 v[32:33], v[32:33], 0, s[52:53]
	s_nop 0
	s_waitcnt vmcnt(0)
	v_mov_b32_e32 v28, v216
	v_mov_b32_e32 v29, v217
	v_mov_b32_e32 v30, v218
	v_mov_b32_e32 v31, v219
	v_mov_b32_e32 v36, v220
	v_mov_b32_e32 v37, v221
	v_mov_b32_e32 v38, v222
	v_mov_b32_e32 v39, v223
	v_bfe_u32 v32, v28, 16, 1
	v_bfe_u32 v40, v30, 16, 1
	v_bfe_u32 v42, v36, 16, 1
	v_bfe_u32 v44, v38, 16, 1
	v_bfe_u32 v33, v29, 16, 1
	v_bfe_u32 v41, v31, 16, 1
	v_bfe_u32 v43, v37, 16, 1
	v_bfe_u32 v45, v39, 16, 1
	v_add3_u32 v28, v28, v32, s33
	v_add3_u32 v30, v30, v40, s33
	v_add3_u32 v32, v36, v42, s33
	v_add3_u32 v36, v38, v44, s33
	v_add3_u32 v29, v29, v33, s33
	v_add3_u32 v31, v31, v41, s33
	v_add3_u32 v33, v37, v43, s33
	v_add3_u32 v37, v39, v45, s33
	v_lshrrev_b32_e32 v28, 16, v28
	v_lshrrev_b32_e32 v30, 16, v30
	v_lshrrev_b32_e32 v32, 16, v32
	v_lshrrev_b32_e32 v36, 16, v36
	v_and_or_b32 v28, v29, s50, v28
	v_and_or_b32 v29, v31, s50, v30
	v_and_or_b32 v30, v33, s50, v32
	v_and_or_b32 v31, v37, s50, v36
